# o19 + 2560 w_in conversion items (LN1 fold, kb>=22) deferred to GU1 idle workgroups with a hand-written 2-blocks-per-pull fold converter; v66-129 parked in LDS
# baseline (speedup 1.0000x reference)
.LBB0_7:
	s_or_b64 exec, exec, s[14:15]
	s_movk_i32 s93, 0x1600
	v_cmp_gt_i32_e64 s[94:95], s93, v176
	v_add_u32_e32 v176, s42, v176
	v_cmp_le_i32_e64 s[66:67], s93, v176
	v_mov_b32_e32 v177, 0xb00
	s_and_b64 vcc, s[94:95], s[66:67]
	s_nop 1
	v_cndmask_b32_e32 v177, 0, v177, vcc
	v_add_u32_e32 v176, v176, v177
	v_lshl_add_u32 v170, v177, 3, v170
	s_movk_i32 s93, 0x3700
	v_sub_u32_e32 v177, v176, v177
	v_subrev_u32_e32 v177, s42, v177
	v_cmp_gt_i32_e64 s[94:95], s93, v177
	v_cmp_le_i32_e64 s[66:67], s93, v176
	v_mov_b32_e32 v177, 0xa00
	s_and_b64 vcc, s[94:95], s[66:67]
	s_nop 1
	v_cndmask_b32_e32 v177, 0, v177, vcc
	v_add_u32_e32 v176, v176, v177
	v_lshl_add_u32 v170, v177, 3, v170
	v_cmp_lt_i32_e32 vcc, s65, v176
	s_or_b64 s[34:35], vcc, s[34:35]
	v_add_u32_e32 v170, s33, v170
	s_andn2_b64 exec, exec, s[34:35]
	s_cbranch_execz .LBB0_115

.Lw1d_go:
	v_lshlrev_b32_e32 v6, 4, v0
	v_add_u32_e32 v7, 0x10000, v6
	ds_write_b128 v6, v[66:69] offset:0
	ds_write_b128 v6, v[70:73] offset:8192
	ds_write_b128 v6, v[74:77] offset:16384
	ds_write_b128 v6, v[78:81] offset:24576
	ds_write_b128 v6, v[82:85] offset:32768
	ds_write_b128 v6, v[86:89] offset:40960
	ds_write_b128 v6, v[90:93] offset:49152
	ds_write_b128 v6, v[94:97] offset:57344
	ds_write_b128 v7, v[98:101] offset:0
	ds_write_b128 v7, v[102:105] offset:8192
	ds_write_b128 v7, v[106:109] offset:16384
	ds_write_b128 v7, v[110:113] offset:24576
	ds_write_b128 v7, v[114:117] offset:32768
	ds_write_b128 v7, v[118:121] offset:40960
	ds_write_b128 v7, v[122:125] offset:49152
	ds_write_b128 v7, v[126:129] offset:57344
	v_readlane_b32 s0, v253, 21
	v_readlane_b32 s1, v253, 22
	s_nop 3
	s_sub_u32 s0, s0, 0xe0
	s_subb_u32 s1, s1, 0
	s_load_dwordx8 s[56:63], s[0:1], 0x50
	s_add_u32 s6, s86, 0xc600
	s_addc_u32 s7, s87, 0
	s_add_u32 s64, s86, 0x32000
	s_addc_u32 s65, s87, 0
	s_add_u32 s66, s86, 0x43000
	s_addc_u32 s67, s87, 0
	s_add_u32 s68, s86, 0x4360200
	s_addc_u32 s69, s87, 0
	s_waitcnt lgkmcnt(0)
	v_and_b32_e32 v6, 15, v0
	v_and_b32_e32 v7, 48, v0
	v_lshlrev_b32_e32 v8, 13, v7
	v_lshl_or_b32 v8, v6, 4, v8
	v_lshlrev_b32_e32 v9, 2, v6
	v_and_b32_e32 v9, 32, v9
	v_lshlrev_b32_e32 v10, 4, v6
	v_and_b32_e32 v10, 16, v10
	v_lshlrev_b32_e32 v11, 1, v6
	v_and_b32_e32 v11, 12, v11
	v_or3_b32 v45, v9, v10, v11
	v_lshlrev_b32_e32 v46, 2, v6
	v_mul_u32_u24_e32 v9, 0x2c00, v45
	v_lshl_add_u32 v12, v7, 1, v9
	v_add_u32_e32 v13, 0x2c00, v12
	v_add_u32_e32 v14, 0x5800, v12
	v_add_u32_e32 v15, 0x8400, v12
	v_mul_u32_u24_e32 v44, 0x101c0, v7
	v_lshl_add_u32 v44, v6, 4, v44
	v_lshlrev_b32_e32 v47, 2, v7
	v_and_b32_e32 v19, 63, v0
	v_xor_b32_e32 v48, 16, v19
	v_lshlrev_b32_e32 v48, 2, v48
	v_xor_b32_e32 v1, 32, v19
	v_lshlrev_b32_e32 v1, 2, v1
	v_cmp_gt_u32_e64 s[36:37], 16, v19
	v_cmp_gt_u32_e64 s[38:39], 8, v6
	v_mov_b32_e32 v16, 0
	v_mov_b32_e32 v17, 1
	s_mov_b64 exec, 1
	global_atomic_add v18, v16, v17, s[6:7] sc0
	s_mov_b64 exec, -1
	s_waitcnt vmcnt(0)
.Lw1d_loop:
	v_readfirstlane_b32 s98, v18
	s_nop 3
	s_cmpk_ge_u32 s98, 0xa80
	s_cbranch_scc1 .Lw1d_done2
	s_cmpk_ge_u32 s98, 0x500
	s_cbranch_scc1 .Lw1d_item
	s_lshl_b32 s99, s98, 1
	s_add_u32 s99, s99, 0x1600
	s_lshr_b32 s100, s99, 8
	s_and_b32 s101, s99, 0xff
	s_lshl_b32 s70, s101, 6
	s_cmpk_gt_u32 s101, 0x3f
	s_cselect_b32 s71, 0x50, 0
	s_cmpk_gt_u32 s101, 0x9f
	s_cselect_b32 s71, 0x70, s71
	s_add_u32 s70, s70, s71
	s_lshl_b32 s70, s70, 2
	s_mul_i32 s71, s100, 0x407000
	s_add_u32 s70, s70, s71
	s_add_u32 s0, s62, s70
	s_addc_u32 s1, s63, 0
	s_lshl_b32 s70, s101, 18
	s_lshl_b32 s71, s100, 7
	s_add_u32 s70, s70, s71
	s_add_u32 s2, s68, s70
	s_addc_u32 s3, s69, 0
	s_add_u32 s4, s2, 0x40000
	s_addc_u32 s5, s3, 0
	s_lshl_b32 s70, s101, 8
	s_add_u32 s72, s64, s70
	s_addc_u32 s73, s65, 0
	s_add_u32 s74, s66, s70
	s_addc_u32 s75, s67, 0
	s_add_u32 s76, s72, 0x100
	s_addc_u32 s77, s73, 0
	s_add_u32 s78, s74, 0x100
	s_addc_u32 s79, s75, 0
	s_lshl_b32 s70, s100, 8
	s_add_u32 s10, s58, s70
	s_addc_u32 s11, s59, 0
	s_add_u32 s32, s60, s70
	s_addc_u32 s33, s61, 0
	s_lshr_b32 s70, s101, 2
	s_sub_u32 s71, s70, 12
	s_cmpk_lt_u32 s71, 4
	s_cselect_b64 s[40:41], s[38:39], 0
	s_cmpk_lt_u32 s70, 10
	s_cselect_b64 s[34:35], s[38:39], s[40:41]
	s_mov_b64 vcc, s[34:35]
	s_nop 1
	v_cndmask_b32_e32 v122, v45, v46, vcc
	s_mov_b64 vcc, s[40:41]
	s_nop 1
	v_cndmask_b32_e32 v123, v45, v46, vcc
	global_load_dwordx4 v[66:69], v47, s[10:11] offset:0
	global_load_dwordx4 v[82:85], v47, s[32:33] offset:0
	global_load_dwordx4 v[70:73], v47, s[10:11] offset:16
	global_load_dwordx4 v[86:89], v47, s[32:33] offset:16
	global_load_dwordx4 v[74:77], v47, s[10:11] offset:32
	global_load_dwordx4 v[90:93], v47, s[32:33] offset:32
	global_load_dwordx4 v[78:81], v47, s[10:11] offset:48
	global_load_dwordx4 v[94:97], v47, s[32:33] offset:48
	global_load_dwordx4 v[154:157], v44, s[0:1] nt
	global_load_dwordx4 v[204:207], v44, s[0:1] offset:256 nt
	s_add_u32 s0, s0, 0x101c0
	s_addc_u32 s1, s1, 0
	global_load_dwordx4 v[158:161], v44, s[0:1] nt
	global_load_dwordx4 v[208:211], v44, s[0:1] offset:256 nt
	s_add_u32 s0, s0, 0x101c0
	s_addc_u32 s1, s1, 0
	global_load_dwordx4 v[162:165], v44, s[0:1] nt
	global_load_dwordx4 v[212:215], v44, s[0:1] offset:256 nt
	s_add_u32 s0, s0, 0x101c0
	s_addc_u32 s1, s1, 0
	global_load_dwordx4 v[166:169], v44, s[0:1] nt
	global_load_dwordx4 v[216:219], v44, s[0:1] offset:256 nt
	s_add_u32 s0, s0, 0x101c0
	s_addc_u32 s1, s1, 0
	global_load_dwordx4 v[170:173], v44, s[0:1] nt
	global_load_dwordx4 v[220:223], v44, s[0:1] offset:256 nt
	s_add_u32 s0, s0, 0x101c0
	s_addc_u32 s1, s1, 0
	global_load_dwordx4 v[174:177], v44, s[0:1] nt
	global_load_dwordx4 v[224:227], v44, s[0:1] offset:256 nt
	s_add_u32 s0, s0, 0x101c0
	s_addc_u32 s1, s1, 0
	global_load_dwordx4 v[178:181], v44, s[0:1] nt
	global_load_dwordx4 v[228:231], v44, s[0:1] offset:256 nt
	s_add_u32 s0, s0, 0x101c0
	s_addc_u32 s1, s1, 0
	global_load_dwordx4 v[182:185], v44, s[0:1] nt
	global_load_dwordx4 v[232:235], v44, s[0:1] offset:256 nt
	s_add_u32 s0, s0, 0x101c0
	s_addc_u32 s1, s1, 0
	global_load_dwordx4 v[186:189], v44, s[0:1] nt
	global_load_dwordx4 v[236:239], v44, s[0:1] offset:256 nt
	s_add_u32 s0, s0, 0x101c0
	s_addc_u32 s1, s1, 0
	global_load_dwordx4 v[190:193], v44, s[0:1] nt
	global_load_dwordx4 v[240:243], v44, s[0:1] offset:256 nt
	s_add_u32 s0, s0, 0x101c0
	s_addc_u32 s1, s1, 0
	global_load_dwordx4 v[194:197], v44, s[0:1] nt
	global_load_dwordx4 v[244:247], v44, s[0:1] offset:256 nt
	s_add_u32 s0, s0, 0x101c0
	s_addc_u32 s1, s1, 0
	global_load_dwordx4 v[198:201], v44, s[0:1] nt
	global_load_dwordx4 v[248:251], v44, s[0:1] offset:256 nt
	s_add_u32 s0, s0, 0x101c0
	s_addc_u32 s1, s1, 0
	global_load_dwordx4 v[130:133], v44, s[0:1] nt
	global_load_dwordx4 v[50:53], v44, s[0:1] offset:256 nt
	s_add_u32 s0, s0, 0x101c0
	s_addc_u32 s1, s1, 0
	global_load_dwordx4 v[134:137], v44, s[0:1] nt
	global_load_dwordx4 v[54:57], v44, s[0:1] offset:256 nt
	s_add_u32 s0, s0, 0x101c0
	s_addc_u32 s1, s1, 0
	global_load_dwordx4 v[138:141], v44, s[0:1] nt
	global_load_dwordx4 v[58:61], v44, s[0:1] offset:256 nt
	s_add_u32 s0, s0, 0x101c0
	s_addc_u32 s1, s1, 0
	global_load_dwordx4 v[142:145], v44, s[0:1] nt
	global_load_dwordx4 v[62:65], v44, s[0:1] offset:256 nt
	s_mov_b64 exec, 1
	global_atomic_add v18, v16, v17, s[6:7] sc0
	s_mov_b64 exec, -1
	s_waitcnt vmcnt(1)
	v_mul_f32_e32 v98, v154, v82
	v_mul_f32_e32 v99, v155, v82
	v_mul_f32_e32 v100, v156, v82
	v_mul_f32_e32 v101, v157, v82
	v_mul_f32_e32 v154, v154, v66
	v_mul_f32_e32 v155, v155, v66
	v_mul_f32_e32 v156, v156, v66
	v_mul_f32_e32 v157, v157, v66
	v_fmac_f32_e32 v98, v158, v83
	v_fmac_f32_e32 v99, v159, v83
	v_fmac_f32_e32 v100, v160, v83
	v_fmac_f32_e32 v101, v161, v83
	v_mul_f32_e32 v158, v158, v67
	v_mul_f32_e32 v159, v159, v67
	v_mul_f32_e32 v160, v160, v67
	v_mul_f32_e32 v161, v161, v67
	v_fmac_f32_e32 v98, v162, v84
	v_fmac_f32_e32 v99, v163, v84
	v_fmac_f32_e32 v100, v164, v84
	v_fmac_f32_e32 v101, v165, v84
	v_mul_f32_e32 v162, v162, v68
	v_mul_f32_e32 v163, v163, v68
	v_mul_f32_e32 v164, v164, v68
	v_mul_f32_e32 v165, v165, v68
	v_fmac_f32_e32 v98, v166, v85
	v_fmac_f32_e32 v99, v167, v85
	v_fmac_f32_e32 v100, v168, v85
	v_fmac_f32_e32 v101, v169, v85
	v_mul_f32_e32 v166, v166, v69
	v_mul_f32_e32 v167, v167, v69
	v_mul_f32_e32 v168, v168, v69
	v_mul_f32_e32 v169, v169, v69
	v_fmac_f32_e32 v98, v170, v86
	v_fmac_f32_e32 v99, v171, v86
	v_fmac_f32_e32 v100, v172, v86
	v_fmac_f32_e32 v101, v173, v86
	v_mul_f32_e32 v170, v170, v70
	v_mul_f32_e32 v171, v171, v70
	v_mul_f32_e32 v172, v172, v70
	v_mul_f32_e32 v173, v173, v70
	v_fmac_f32_e32 v98, v174, v87
	v_fmac_f32_e32 v99, v175, v87
	v_fmac_f32_e32 v100, v176, v87
	v_fmac_f32_e32 v101, v177, v87
	v_mul_f32_e32 v174, v174, v71
	v_mul_f32_e32 v175, v175, v71
	v_mul_f32_e32 v176, v176, v71
	v_mul_f32_e32 v177, v177, v71
	v_fmac_f32_e32 v98, v178, v88
	v_fmac_f32_e32 v99, v179, v88
	v_fmac_f32_e32 v100, v180, v88
	v_fmac_f32_e32 v101, v181, v88
	v_mul_f32_e32 v178, v178, v72
	v_mul_f32_e32 v179, v179, v72
	v_mul_f32_e32 v180, v180, v72
	v_mul_f32_e32 v181, v181, v72
	v_fmac_f32_e32 v98, v182, v89
	v_fmac_f32_e32 v99, v183, v89
	v_fmac_f32_e32 v100, v184, v89
	v_fmac_f32_e32 v101, v185, v89
	v_mul_f32_e32 v182, v182, v73
	v_mul_f32_e32 v183, v183, v73
	v_mul_f32_e32 v184, v184, v73
	v_mul_f32_e32 v185, v185, v73
	v_fmac_f32_e32 v98, v186, v90
	v_fmac_f32_e32 v99, v187, v90
	v_fmac_f32_e32 v100, v188, v90
	v_fmac_f32_e32 v101, v189, v90
	v_mul_f32_e32 v186, v186, v74
	v_mul_f32_e32 v187, v187, v74
	v_mul_f32_e32 v188, v188, v74
	v_mul_f32_e32 v189, v189, v74
	v_fmac_f32_e32 v98, v190, v91
	v_fmac_f32_e32 v99, v191, v91
	v_fmac_f32_e32 v100, v192, v91
	v_fmac_f32_e32 v101, v193, v91
	v_mul_f32_e32 v190, v190, v75
	v_mul_f32_e32 v191, v191, v75
	v_mul_f32_e32 v192, v192, v75
	v_mul_f32_e32 v193, v193, v75
	v_fmac_f32_e32 v98, v194, v92
	v_fmac_f32_e32 v99, v195, v92
	v_fmac_f32_e32 v100, v196, v92
	v_fmac_f32_e32 v101, v197, v92
	v_mul_f32_e32 v194, v194, v76
	v_mul_f32_e32 v195, v195, v76
	v_mul_f32_e32 v196, v196, v76
	v_mul_f32_e32 v197, v197, v76
	v_fmac_f32_e32 v98, v198, v93
	v_fmac_f32_e32 v99, v199, v93
	v_fmac_f32_e32 v100, v200, v93
	v_fmac_f32_e32 v101, v201, v93
	v_mul_f32_e32 v198, v198, v77
	v_mul_f32_e32 v199, v199, v77
	v_mul_f32_e32 v200, v200, v77
	v_mul_f32_e32 v201, v201, v77
	v_fmac_f32_e32 v98, v130, v94
	v_fmac_f32_e32 v99, v131, v94
	v_fmac_f32_e32 v100, v132, v94
	v_fmac_f32_e32 v101, v133, v94
	v_mul_f32_e32 v130, v130, v78
	v_mul_f32_e32 v131, v131, v78
	v_mul_f32_e32 v132, v132, v78
	v_mul_f32_e32 v133, v133, v78
	v_fmac_f32_e32 v98, v134, v95
	v_fmac_f32_e32 v99, v135, v95
	v_fmac_f32_e32 v100, v136, v95
	v_fmac_f32_e32 v101, v137, v95
	v_mul_f32_e32 v134, v134, v79
	v_mul_f32_e32 v135, v135, v79
	v_mul_f32_e32 v136, v136, v79
	v_mul_f32_e32 v137, v137, v79
	v_fmac_f32_e32 v98, v138, v96
	v_fmac_f32_e32 v99, v139, v96
	v_fmac_f32_e32 v100, v140, v96
	v_fmac_f32_e32 v101, v141, v96
	v_mul_f32_e32 v138, v138, v80
	v_mul_f32_e32 v139, v139, v80
	v_mul_f32_e32 v140, v140, v80
	v_mul_f32_e32 v141, v141, v80
	v_fmac_f32_e32 v98, v142, v97
	v_fmac_f32_e32 v99, v143, v97
	v_fmac_f32_e32 v100, v144, v97
	v_fmac_f32_e32 v101, v145, v97
	v_mul_f32_e32 v142, v142, v81
	v_mul_f32_e32 v143, v143, v81
	v_mul_f32_e32 v144, v144, v81
	v_mul_f32_e32 v145, v145, v81
	v_lshlrev_b32_e32 v2, 2, v122
	v_lshlrev_b32_e32 v3, 12, v122
	v_lshl_add_u32 v3, v7, 1, v3
	ds_bpermute_b32 v106, v48, v98
	ds_bpermute_b32 v107, v48, v99
	ds_bpermute_b32 v108, v48, v100
	ds_bpermute_b32 v109, v48, v101
	s_waitcnt lgkmcnt(0)
	v_add_f32_e32 v98, v98, v106
	v_add_f32_e32 v99, v99, v107
	v_add_f32_e32 v100, v100, v108
	v_add_f32_e32 v101, v101, v109
	ds_bpermute_b32 v106, v1, v98
	ds_bpermute_b32 v107, v1, v99
	ds_bpermute_b32 v108, v1, v100
	ds_bpermute_b32 v109, v1, v101
	s_waitcnt lgkmcnt(0)
	v_add_f32_e32 v98, v98, v106
	v_add_f32_e32 v99, v99, v107
	v_add_f32_e32 v100, v100, v108
	v_add_f32_e32 v101, v101, v109
	s_mov_b64 exec, s[36:37]
	global_atomic_add_f32 v2, v98, s[74:75] offset:0
	global_atomic_add_f32 v2, v99, s[74:75] offset:4
	global_atomic_add_f32 v2, v100, s[74:75] offset:8
	global_atomic_add_f32 v2, v101, s[74:75] offset:12
	s_mov_b64 exec, -1
	v_cvt_pk_bf16_f32 v20, v154, v158
	v_cvt_pk_bf16_f32 v21, v162, v166
	v_cvt_pk_bf16_f32 v22, v170, v174
	v_cvt_pk_bf16_f32 v23, v178, v182
	global_store_dwordx4 v3, v[20:23], s[2:3]
	v_cvt_pk_bf16_f32 v24, v186, v190
	v_cvt_pk_bf16_f32 v25, v194, v198
	v_cvt_pk_bf16_f32 v26, v130, v134
	v_cvt_pk_bf16_f32 v27, v138, v142
	global_store_dwordx4 v3, v[24:27], s[2:3] offset:16
	v_lshlrev_b32_e32 v19, 16, v20
	v_and_b32_e32 v114, 0xffff0000, v20
	v_add_f32_e32 v114, v19, v114
	v_lshlrev_b32_e32 v19, 16, v21
	v_and_b32_e32 v115, 0xffff0000, v21
	v_add_f32_e32 v115, v19, v115
	v_lshlrev_b32_e32 v19, 16, v22
	v_and_b32_e32 v116, 0xffff0000, v22
	v_add_f32_e32 v116, v19, v116
	v_lshlrev_b32_e32 v19, 16, v23
	v_and_b32_e32 v117, 0xffff0000, v23
	v_add_f32_e32 v117, v19, v117
	v_lshlrev_b32_e32 v19, 16, v24
	v_and_b32_e32 v118, 0xffff0000, v24
	v_add_f32_e32 v118, v19, v118
	v_lshlrev_b32_e32 v19, 16, v25
	v_and_b32_e32 v119, 0xffff0000, v25
	v_add_f32_e32 v119, v19, v119
	v_lshlrev_b32_e32 v19, 16, v26
	v_and_b32_e32 v120, 0xffff0000, v26
	v_add_f32_e32 v120, v19, v120
	v_lshlrev_b32_e32 v19, 16, v27
	v_and_b32_e32 v121, 0xffff0000, v27
	v_add_f32_e32 v121, v19, v121
	v_add_f32_e32 v114, v114, v115
	v_add_f32_e32 v116, v116, v117
	v_add_f32_e32 v118, v118, v119
	v_add_f32_e32 v120, v120, v121
	v_add_f32_e32 v114, v114, v116
	v_add_f32_e32 v118, v118, v120
	v_add_f32_e32 v110, v114, v118
	s_add_u32 s2, s2, 0x1000
	s_addc_u32 s3, s3, 0
	v_cvt_pk_bf16_f32 v28, v155, v159
	v_cvt_pk_bf16_f32 v29, v163, v167
	v_cvt_pk_bf16_f32 v30, v171, v175
	v_cvt_pk_bf16_f32 v31, v179, v183
	global_store_dwordx4 v3, v[28:31], s[2:3]
	v_cvt_pk_bf16_f32 v32, v187, v191
	v_cvt_pk_bf16_f32 v33, v195, v199
	v_cvt_pk_bf16_f32 v34, v131, v135
	v_cvt_pk_bf16_f32 v35, v139, v143
	global_store_dwordx4 v3, v[32:35], s[2:3] offset:16
	v_lshlrev_b32_e32 v19, 16, v28
	v_and_b32_e32 v114, 0xffff0000, v28
	v_add_f32_e32 v114, v19, v114
	v_lshlrev_b32_e32 v19, 16, v29
	v_and_b32_e32 v115, 0xffff0000, v29
	v_add_f32_e32 v115, v19, v115
	v_lshlrev_b32_e32 v19, 16, v30
	v_and_b32_e32 v116, 0xffff0000, v30
	v_add_f32_e32 v116, v19, v116
	v_lshlrev_b32_e32 v19, 16, v31
	v_and_b32_e32 v117, 0xffff0000, v31
	v_add_f32_e32 v117, v19, v117
	v_lshlrev_b32_e32 v19, 16, v32
	v_and_b32_e32 v118, 0xffff0000, v32
	v_add_f32_e32 v118, v19, v118
	v_lshlrev_b32_e32 v19, 16, v33
	v_and_b32_e32 v119, 0xffff0000, v33
	v_add_f32_e32 v119, v19, v119
	v_lshlrev_b32_e32 v19, 16, v34
	v_and_b32_e32 v120, 0xffff0000, v34
	v_add_f32_e32 v120, v19, v120
	v_lshlrev_b32_e32 v19, 16, v35
	v_and_b32_e32 v121, 0xffff0000, v35
	v_add_f32_e32 v121, v19, v121
	v_add_f32_e32 v114, v114, v115
	v_add_f32_e32 v116, v116, v117
	v_add_f32_e32 v118, v118, v119
	v_add_f32_e32 v120, v120, v121
	v_add_f32_e32 v114, v114, v116
	v_add_f32_e32 v118, v118, v120
	v_add_f32_e32 v111, v114, v118
	s_add_u32 s2, s2, 0x1000
	s_addc_u32 s3, s3, 0
	v_cvt_pk_bf16_f32 v36, v156, v160
	v_cvt_pk_bf16_f32 v37, v164, v168
	v_cvt_pk_bf16_f32 v38, v172, v176
	v_cvt_pk_bf16_f32 v39, v180, v184
	global_store_dwordx4 v3, v[36:39], s[2:3]
	v_cvt_pk_bf16_f32 v40, v188, v192
	v_cvt_pk_bf16_f32 v41, v196, v200
	v_cvt_pk_bf16_f32 v42, v132, v136
	v_cvt_pk_bf16_f32 v43, v140, v144
	global_store_dwordx4 v3, v[40:43], s[2:3] offset:16
	v_lshlrev_b32_e32 v19, 16, v36
	v_and_b32_e32 v114, 0xffff0000, v36
	v_add_f32_e32 v114, v19, v114
	v_lshlrev_b32_e32 v19, 16, v37
	v_and_b32_e32 v115, 0xffff0000, v37
	v_add_f32_e32 v115, v19, v115
	v_lshlrev_b32_e32 v19, 16, v38
	v_and_b32_e32 v116, 0xffff0000, v38
	v_add_f32_e32 v116, v19, v116
	v_lshlrev_b32_e32 v19, 16, v39
	v_and_b32_e32 v117, 0xffff0000, v39
	v_add_f32_e32 v117, v19, v117
	v_lshlrev_b32_e32 v19, 16, v40
	v_and_b32_e32 v118, 0xffff0000, v40
	v_add_f32_e32 v118, v19, v118
	v_lshlrev_b32_e32 v19, 16, v41
	v_and_b32_e32 v119, 0xffff0000, v41
	v_add_f32_e32 v119, v19, v119
	v_lshlrev_b32_e32 v19, 16, v42
	v_and_b32_e32 v120, 0xffff0000, v42
	v_add_f32_e32 v120, v19, v120
	v_lshlrev_b32_e32 v19, 16, v43
	v_and_b32_e32 v121, 0xffff0000, v43
	v_add_f32_e32 v121, v19, v121
	v_add_f32_e32 v114, v114, v115
	v_add_f32_e32 v116, v116, v117
	v_add_f32_e32 v118, v118, v119
	v_add_f32_e32 v120, v120, v121
	v_add_f32_e32 v114, v114, v116
	v_add_f32_e32 v118, v118, v120
	v_add_f32_e32 v112, v114, v118
	s_add_u32 s2, s2, 0x1000
	s_addc_u32 s3, s3, 0
	v_cvt_pk_bf16_f32 v20, v157, v161
	v_cvt_pk_bf16_f32 v21, v165, v169
	v_cvt_pk_bf16_f32 v22, v173, v177
	v_cvt_pk_bf16_f32 v23, v181, v185
	global_store_dwordx4 v3, v[20:23], s[2:3]
	v_cvt_pk_bf16_f32 v24, v189, v193
	v_cvt_pk_bf16_f32 v25, v197, v201
	v_cvt_pk_bf16_f32 v26, v133, v137
	v_cvt_pk_bf16_f32 v27, v141, v145
	global_store_dwordx4 v3, v[24:27], s[2:3] offset:16
	v_lshlrev_b32_e32 v19, 16, v20
	v_and_b32_e32 v114, 0xffff0000, v20
	v_add_f32_e32 v114, v19, v114
	v_lshlrev_b32_e32 v19, 16, v21
	v_and_b32_e32 v115, 0xffff0000, v21
	v_add_f32_e32 v115, v19, v115
	v_lshlrev_b32_e32 v19, 16, v22
	v_and_b32_e32 v116, 0xffff0000, v22
	v_add_f32_e32 v116, v19, v116
	v_lshlrev_b32_e32 v19, 16, v23
	v_and_b32_e32 v117, 0xffff0000, v23
	v_add_f32_e32 v117, v19, v117
	v_lshlrev_b32_e32 v19, 16, v24
	v_and_b32_e32 v118, 0xffff0000, v24
	v_add_f32_e32 v118, v19, v118
	v_lshlrev_b32_e32 v19, 16, v25
	v_and_b32_e32 v119, 0xffff0000, v25
	v_add_f32_e32 v119, v19, v119
	v_lshlrev_b32_e32 v19, 16, v26
	v_and_b32_e32 v120, 0xffff0000, v26
	v_add_f32_e32 v120, v19, v120
	v_lshlrev_b32_e32 v19, 16, v27
	v_and_b32_e32 v121, 0xffff0000, v27
	v_add_f32_e32 v121, v19, v121
	v_add_f32_e32 v114, v114, v115
	v_add_f32_e32 v116, v116, v117
	v_add_f32_e32 v118, v118, v119
	v_add_f32_e32 v120, v120, v121
	v_add_f32_e32 v114, v114, v116
	v_add_f32_e32 v118, v118, v120
	v_add_f32_e32 v113, v114, v118
	ds_bpermute_b32 v106, v48, v110
	ds_bpermute_b32 v107, v48, v111
	ds_bpermute_b32 v108, v48, v112
	ds_bpermute_b32 v109, v48, v113
	s_waitcnt lgkmcnt(0)
	v_add_f32_e32 v110, v110, v106
	v_add_f32_e32 v111, v111, v107
	v_add_f32_e32 v112, v112, v108
	v_add_f32_e32 v113, v113, v109
	ds_bpermute_b32 v106, v1, v110
	ds_bpermute_b32 v107, v1, v111
	ds_bpermute_b32 v108, v1, v112
	ds_bpermute_b32 v109, v1, v113
	s_waitcnt lgkmcnt(0)
	v_add_f32_e32 v110, v110, v106
	v_add_f32_e32 v111, v111, v107
	v_add_f32_e32 v112, v112, v108
	v_add_f32_e32 v113, v113, v109
	s_mov_b64 exec, s[36:37]
	global_atomic_add_f32 v2, v110, s[72:73] offset:0
	global_atomic_add_f32 v2, v111, s[72:73] offset:4
	global_atomic_add_f32 v2, v112, s[72:73] offset:8
	global_atomic_add_f32 v2, v113, s[72:73] offset:12
	s_mov_b64 exec, -1
	v_mul_f32_e32 v98, v204, v82
	v_mul_f32_e32 v99, v205, v82
	v_mul_f32_e32 v100, v206, v82
	v_mul_f32_e32 v101, v207, v82
	v_mul_f32_e32 v204, v204, v66
	v_mul_f32_e32 v205, v205, v66
	v_mul_f32_e32 v206, v206, v66
	v_mul_f32_e32 v207, v207, v66
	v_fmac_f32_e32 v98, v208, v83
	v_fmac_f32_e32 v99, v209, v83
	v_fmac_f32_e32 v100, v210, v83
	v_fmac_f32_e32 v101, v211, v83
	v_mul_f32_e32 v208, v208, v67
	v_mul_f32_e32 v209, v209, v67
	v_mul_f32_e32 v210, v210, v67
	v_mul_f32_e32 v211, v211, v67
	v_fmac_f32_e32 v98, v212, v84
	v_fmac_f32_e32 v99, v213, v84
	v_fmac_f32_e32 v100, v214, v84
	v_fmac_f32_e32 v101, v215, v84
	v_mul_f32_e32 v212, v212, v68
	v_mul_f32_e32 v213, v213, v68
	v_mul_f32_e32 v214, v214, v68
	v_mul_f32_e32 v215, v215, v68
	v_fmac_f32_e32 v98, v216, v85
	v_fmac_f32_e32 v99, v217, v85
	v_fmac_f32_e32 v100, v218, v85
	v_fmac_f32_e32 v101, v219, v85
	v_mul_f32_e32 v216, v216, v69
	v_mul_f32_e32 v217, v217, v69
	v_mul_f32_e32 v218, v218, v69
	v_mul_f32_e32 v219, v219, v69
	v_fmac_f32_e32 v98, v220, v86
	v_fmac_f32_e32 v99, v221, v86
	v_fmac_f32_e32 v100, v222, v86
	v_fmac_f32_e32 v101, v223, v86
	v_mul_f32_e32 v220, v220, v70
	v_mul_f32_e32 v221, v221, v70
	v_mul_f32_e32 v222, v222, v70
	v_mul_f32_e32 v223, v223, v70
	v_fmac_f32_e32 v98, v224, v87
	v_fmac_f32_e32 v99, v225, v87
	v_fmac_f32_e32 v100, v226, v87
	v_fmac_f32_e32 v101, v227, v87
	v_mul_f32_e32 v224, v224, v71
	v_mul_f32_e32 v225, v225, v71
	v_mul_f32_e32 v226, v226, v71
	v_mul_f32_e32 v227, v227, v71
	v_fmac_f32_e32 v98, v228, v88
	v_fmac_f32_e32 v99, v229, v88
	v_fmac_f32_e32 v100, v230, v88
	v_fmac_f32_e32 v101, v231, v88
	v_mul_f32_e32 v228, v228, v72
	v_mul_f32_e32 v229, v229, v72
	v_mul_f32_e32 v230, v230, v72
	v_mul_f32_e32 v231, v231, v72
	v_fmac_f32_e32 v98, v232, v89
	v_fmac_f32_e32 v99, v233, v89
	v_fmac_f32_e32 v100, v234, v89
	v_fmac_f32_e32 v101, v235, v89
	v_mul_f32_e32 v232, v232, v73
	v_mul_f32_e32 v233, v233, v73
	v_mul_f32_e32 v234, v234, v73
	v_mul_f32_e32 v235, v235, v73
	v_fmac_f32_e32 v98, v236, v90
	v_fmac_f32_e32 v99, v237, v90
	v_fmac_f32_e32 v100, v238, v90
	v_fmac_f32_e32 v101, v239, v90
	v_mul_f32_e32 v236, v236, v74
	v_mul_f32_e32 v237, v237, v74
	v_mul_f32_e32 v238, v238, v74
	v_mul_f32_e32 v239, v239, v74
	v_fmac_f32_e32 v98, v240, v91
	v_fmac_f32_e32 v99, v241, v91
	v_fmac_f32_e32 v100, v242, v91
	v_fmac_f32_e32 v101, v243, v91
	v_mul_f32_e32 v240, v240, v75
	v_mul_f32_e32 v241, v241, v75
	v_mul_f32_e32 v242, v242, v75
	v_mul_f32_e32 v243, v243, v75
	v_fmac_f32_e32 v98, v244, v92
	v_fmac_f32_e32 v99, v245, v92
	v_fmac_f32_e32 v100, v246, v92
	v_fmac_f32_e32 v101, v247, v92
	v_mul_f32_e32 v244, v244, v76
	v_mul_f32_e32 v245, v245, v76
	v_mul_f32_e32 v246, v246, v76
	v_mul_f32_e32 v247, v247, v76
	v_fmac_f32_e32 v98, v248, v93
	v_fmac_f32_e32 v99, v249, v93
	v_fmac_f32_e32 v100, v250, v93
	v_fmac_f32_e32 v101, v251, v93
	v_mul_f32_e32 v248, v248, v77
	v_mul_f32_e32 v249, v249, v77
	v_mul_f32_e32 v250, v250, v77
	v_mul_f32_e32 v251, v251, v77
	v_fmac_f32_e32 v98, v50, v94
	v_fmac_f32_e32 v99, v51, v94
	v_fmac_f32_e32 v100, v52, v94
	v_fmac_f32_e32 v101, v53, v94
	v_mul_f32_e32 v50, v50, v78
	v_mul_f32_e32 v51, v51, v78
	v_mul_f32_e32 v52, v52, v78
	v_mul_f32_e32 v53, v53, v78
	v_fmac_f32_e32 v98, v54, v95
	v_fmac_f32_e32 v99, v55, v95
	v_fmac_f32_e32 v100, v56, v95
	v_fmac_f32_e32 v101, v57, v95
	v_mul_f32_e32 v54, v54, v79
	v_mul_f32_e32 v55, v55, v79
	v_mul_f32_e32 v56, v56, v79
	v_mul_f32_e32 v57, v57, v79
	v_fmac_f32_e32 v98, v58, v96
	v_fmac_f32_e32 v99, v59, v96
	v_fmac_f32_e32 v100, v60, v96
	v_fmac_f32_e32 v101, v61, v96
	v_mul_f32_e32 v58, v58, v80
	v_mul_f32_e32 v59, v59, v80
	v_mul_f32_e32 v60, v60, v80
	v_mul_f32_e32 v61, v61, v80
	v_fmac_f32_e32 v98, v62, v97
	v_fmac_f32_e32 v99, v63, v97
	v_fmac_f32_e32 v100, v64, v97
	v_fmac_f32_e32 v101, v65, v97
	v_mul_f32_e32 v62, v62, v81
	v_mul_f32_e32 v63, v63, v81
	v_mul_f32_e32 v64, v64, v81
	v_mul_f32_e32 v65, v65, v81
	v_lshlrev_b32_e32 v2, 2, v123
	v_lshlrev_b32_e32 v3, 12, v123
	v_lshl_add_u32 v3, v7, 1, v3
	ds_bpermute_b32 v106, v48, v98
	ds_bpermute_b32 v107, v48, v99
	ds_bpermute_b32 v108, v48, v100
	ds_bpermute_b32 v109, v48, v101
	s_waitcnt lgkmcnt(0)
	v_add_f32_e32 v98, v98, v106
	v_add_f32_e32 v99, v99, v107
	v_add_f32_e32 v100, v100, v108
	v_add_f32_e32 v101, v101, v109
	ds_bpermute_b32 v106, v1, v98
	ds_bpermute_b32 v107, v1, v99
	ds_bpermute_b32 v108, v1, v100
	ds_bpermute_b32 v109, v1, v101
	s_waitcnt lgkmcnt(0)
	v_add_f32_e32 v98, v98, v106
	v_add_f32_e32 v99, v99, v107
	v_add_f32_e32 v100, v100, v108
	v_add_f32_e32 v101, v101, v109
	s_mov_b64 exec, s[36:37]
	global_atomic_add_f32 v2, v98, s[78:79] offset:0
	global_atomic_add_f32 v2, v99, s[78:79] offset:4
	global_atomic_add_f32 v2, v100, s[78:79] offset:8
	global_atomic_add_f32 v2, v101, s[78:79] offset:12
	s_mov_b64 exec, -1
	v_cvt_pk_bf16_f32 v20, v204, v208
	v_cvt_pk_bf16_f32 v21, v212, v216
	v_cvt_pk_bf16_f32 v22, v220, v224
	v_cvt_pk_bf16_f32 v23, v228, v232
	global_store_dwordx4 v3, v[20:23], s[4:5]
	v_cvt_pk_bf16_f32 v24, v236, v240
	v_cvt_pk_bf16_f32 v25, v244, v248
	v_cvt_pk_bf16_f32 v26, v50, v54
	v_cvt_pk_bf16_f32 v27, v58, v62
	global_store_dwordx4 v3, v[24:27], s[4:5] offset:16
	v_lshlrev_b32_e32 v19, 16, v20
	v_and_b32_e32 v114, 0xffff0000, v20
	v_add_f32_e32 v114, v19, v114
	v_lshlrev_b32_e32 v19, 16, v21
	v_and_b32_e32 v115, 0xffff0000, v21
	v_add_f32_e32 v115, v19, v115
	v_lshlrev_b32_e32 v19, 16, v22
	v_and_b32_e32 v116, 0xffff0000, v22
	v_add_f32_e32 v116, v19, v116
	v_lshlrev_b32_e32 v19, 16, v23
	v_and_b32_e32 v117, 0xffff0000, v23
	v_add_f32_e32 v117, v19, v117
	v_lshlrev_b32_e32 v19, 16, v24
	v_and_b32_e32 v118, 0xffff0000, v24
	v_add_f32_e32 v118, v19, v118
	v_lshlrev_b32_e32 v19, 16, v25
	v_and_b32_e32 v119, 0xffff0000, v25
	v_add_f32_e32 v119, v19, v119
	v_lshlrev_b32_e32 v19, 16, v26
	v_and_b32_e32 v120, 0xffff0000, v26
	v_add_f32_e32 v120, v19, v120
	v_lshlrev_b32_e32 v19, 16, v27
	v_and_b32_e32 v121, 0xffff0000, v27
	v_add_f32_e32 v121, v19, v121
	v_add_f32_e32 v114, v114, v115
	v_add_f32_e32 v116, v116, v117
	v_add_f32_e32 v118, v118, v119
	v_add_f32_e32 v120, v120, v121
	v_add_f32_e32 v114, v114, v116
	v_add_f32_e32 v118, v118, v120
	v_add_f32_e32 v110, v114, v118
	s_add_u32 s4, s4, 0x1000
	s_addc_u32 s5, s5, 0
	v_cvt_pk_bf16_f32 v28, v205, v209
	v_cvt_pk_bf16_f32 v29, v213, v217
	v_cvt_pk_bf16_f32 v30, v221, v225
	v_cvt_pk_bf16_f32 v31, v229, v233
	global_store_dwordx4 v3, v[28:31], s[4:5]
	v_cvt_pk_bf16_f32 v32, v237, v241
	v_cvt_pk_bf16_f32 v33, v245, v249
	v_cvt_pk_bf16_f32 v34, v51, v55
	v_cvt_pk_bf16_f32 v35, v59, v63
	global_store_dwordx4 v3, v[32:35], s[4:5] offset:16
	v_lshlrev_b32_e32 v19, 16, v28
	v_and_b32_e32 v114, 0xffff0000, v28
	v_add_f32_e32 v114, v19, v114
	v_lshlrev_b32_e32 v19, 16, v29
	v_and_b32_e32 v115, 0xffff0000, v29
	v_add_f32_e32 v115, v19, v115
	v_lshlrev_b32_e32 v19, 16, v30
	v_and_b32_e32 v116, 0xffff0000, v30
	v_add_f32_e32 v116, v19, v116
	v_lshlrev_b32_e32 v19, 16, v31
	v_and_b32_e32 v117, 0xffff0000, v31
	v_add_f32_e32 v117, v19, v117
	v_lshlrev_b32_e32 v19, 16, v32
	v_and_b32_e32 v118, 0xffff0000, v32
	v_add_f32_e32 v118, v19, v118
	v_lshlrev_b32_e32 v19, 16, v33
	v_and_b32_e32 v119, 0xffff0000, v33
	v_add_f32_e32 v119, v19, v119
	v_lshlrev_b32_e32 v19, 16, v34
	v_and_b32_e32 v120, 0xffff0000, v34
	v_add_f32_e32 v120, v19, v120
	v_lshlrev_b32_e32 v19, 16, v35
	v_and_b32_e32 v121, 0xffff0000, v35
	v_add_f32_e32 v121, v19, v121
	v_add_f32_e32 v114, v114, v115
	v_add_f32_e32 v116, v116, v117
	v_add_f32_e32 v118, v118, v119
	v_add_f32_e32 v120, v120, v121
	v_add_f32_e32 v114, v114, v116
	v_add_f32_e32 v118, v118, v120
	v_add_f32_e32 v111, v114, v118
	s_add_u32 s4, s4, 0x1000
	s_addc_u32 s5, s5, 0
	v_cvt_pk_bf16_f32 v36, v206, v210
	v_cvt_pk_bf16_f32 v37, v214, v218
	v_cvt_pk_bf16_f32 v38, v222, v226
	v_cvt_pk_bf16_f32 v39, v230, v234
	global_store_dwordx4 v3, v[36:39], s[4:5]
	v_cvt_pk_bf16_f32 v40, v238, v242
	v_cvt_pk_bf16_f32 v41, v246, v250
	v_cvt_pk_bf16_f32 v42, v52, v56
	v_cvt_pk_bf16_f32 v43, v60, v64
	global_store_dwordx4 v3, v[40:43], s[4:5] offset:16
	v_lshlrev_b32_e32 v19, 16, v36
	v_and_b32_e32 v114, 0xffff0000, v36
	v_add_f32_e32 v114, v19, v114
	v_lshlrev_b32_e32 v19, 16, v37
	v_and_b32_e32 v115, 0xffff0000, v37
	v_add_f32_e32 v115, v19, v115
	v_lshlrev_b32_e32 v19, 16, v38
	v_and_b32_e32 v116, 0xffff0000, v38
	v_add_f32_e32 v116, v19, v116
	v_lshlrev_b32_e32 v19, 16, v39
	v_and_b32_e32 v117, 0xffff0000, v39
	v_add_f32_e32 v117, v19, v117
	v_lshlrev_b32_e32 v19, 16, v40
	v_and_b32_e32 v118, 0xffff0000, v40
	v_add_f32_e32 v118, v19, v118
	v_lshlrev_b32_e32 v19, 16, v41
	v_and_b32_e32 v119, 0xffff0000, v41
	v_add_f32_e32 v119, v19, v119
	v_lshlrev_b32_e32 v19, 16, v42
	v_and_b32_e32 v120, 0xffff0000, v42
	v_add_f32_e32 v120, v19, v120
	v_lshlrev_b32_e32 v19, 16, v43
	v_and_b32_e32 v121, 0xffff0000, v43
	v_add_f32_e32 v121, v19, v121
	v_add_f32_e32 v114, v114, v115
	v_add_f32_e32 v116, v116, v117
	v_add_f32_e32 v118, v118, v119
	v_add_f32_e32 v120, v120, v121
	v_add_f32_e32 v114, v114, v116
	v_add_f32_e32 v118, v118, v120
	v_add_f32_e32 v112, v114, v118
	s_add_u32 s4, s4, 0x1000
	s_addc_u32 s5, s5, 0
	v_cvt_pk_bf16_f32 v20, v207, v211
	v_cvt_pk_bf16_f32 v21, v215, v219
	v_cvt_pk_bf16_f32 v22, v223, v227
	v_cvt_pk_bf16_f32 v23, v231, v235
	global_store_dwordx4 v3, v[20:23], s[4:5]
	v_cvt_pk_bf16_f32 v24, v239, v243
	v_cvt_pk_bf16_f32 v25, v247, v251
	v_cvt_pk_bf16_f32 v26, v53, v57
	v_cvt_pk_bf16_f32 v27, v61, v65
	global_store_dwordx4 v3, v[24:27], s[4:5] offset:16
	v_lshlrev_b32_e32 v19, 16, v20
	v_and_b32_e32 v114, 0xffff0000, v20
	v_add_f32_e32 v114, v19, v114
	v_lshlrev_b32_e32 v19, 16, v21
	v_and_b32_e32 v115, 0xffff0000, v21
	v_add_f32_e32 v115, v19, v115
	v_lshlrev_b32_e32 v19, 16, v22
	v_and_b32_e32 v116, 0xffff0000, v22
	v_add_f32_e32 v116, v19, v116
	v_lshlrev_b32_e32 v19, 16, v23
	v_and_b32_e32 v117, 0xffff0000, v23
	v_add_f32_e32 v117, v19, v117
	v_lshlrev_b32_e32 v19, 16, v24
	v_and_b32_e32 v118, 0xffff0000, v24
	v_add_f32_e32 v118, v19, v118
	v_lshlrev_b32_e32 v19, 16, v25
	v_and_b32_e32 v119, 0xffff0000, v25
	v_add_f32_e32 v119, v19, v119
	v_lshlrev_b32_e32 v19, 16, v26
	v_and_b32_e32 v120, 0xffff0000, v26
	v_add_f32_e32 v120, v19, v120
	v_lshlrev_b32_e32 v19, 16, v27
	v_and_b32_e32 v121, 0xffff0000, v27
	v_add_f32_e32 v121, v19, v121
	v_add_f32_e32 v114, v114, v115
	v_add_f32_e32 v116, v116, v117
	v_add_f32_e32 v118, v118, v119
	v_add_f32_e32 v120, v120, v121
	v_add_f32_e32 v114, v114, v116
	v_add_f32_e32 v118, v118, v120
	v_add_f32_e32 v113, v114, v118
	ds_bpermute_b32 v106, v48, v110
	ds_bpermute_b32 v107, v48, v111
	ds_bpermute_b32 v108, v48, v112
	ds_bpermute_b32 v109, v48, v113
	s_waitcnt lgkmcnt(0)
	v_add_f32_e32 v110, v110, v106
	v_add_f32_e32 v111, v111, v107
	v_add_f32_e32 v112, v112, v108
	v_add_f32_e32 v113, v113, v109
	ds_bpermute_b32 v106, v1, v110
	ds_bpermute_b32 v107, v1, v111
	ds_bpermute_b32 v108, v1, v112
	ds_bpermute_b32 v109, v1, v113
	s_waitcnt lgkmcnt(0)
	v_add_f32_e32 v110, v110, v106
	v_add_f32_e32 v111, v111, v107
	v_add_f32_e32 v112, v112, v108
	v_add_f32_e32 v113, v113, v109
	s_mov_b64 exec, s[36:37]
	global_atomic_add_f32 v2, v110, s[76:77] offset:0
	global_atomic_add_f32 v2, v111, s[76:77] offset:4
	global_atomic_add_f32 v2, v112, s[76:77] offset:8
	global_atomic_add_f32 v2, v113, s[76:77] offset:12
	s_mov_b64 exec, -1
	s_waitcnt vmcnt(16)
	s_branch .Lw1d_loop
.Lw1d_item:
	s_sub_u32 s98, s98, 0x500
	s_lshr_b32 s99, s98, 4
	s_and_b32 s100, s98, 15
	s_lshl_b32 s101, s99, 19
	s_lshl_b32 s0, s100, 9
	s_add_u32 s0, s0, s101
	s_add_u32 s0, s56, s0
	s_addc_u32 s1, s57, 0
	s_mul_i32 s2, s100, 0x160000
	s_lshl_b32 s3, s99, 7
	s_add_u32 s2, s2, s3
	s_add_u32 s2, s2, 0x2d60200
	s_add_u32 s2, s86, s2
	s_addc_u32 s3, s87, 0
	s_add_u32 s4, s2, 0xb0000
	s_addc_u32 s5, s3, 0
	global_load_dwordx4 v[154:157], v8, s[0:1] nt
	global_load_dwordx4 v[204:207], v8, s[0:1] offset:256 nt
	s_add_u32 s0, s0, 0x2000
	s_addc_u32 s1, s1, 0
	global_load_dwordx4 v[158:161], v8, s[0:1] nt
	global_load_dwordx4 v[208:211], v8, s[0:1] offset:256 nt
	s_add_u32 s0, s0, 0x2000
	s_addc_u32 s1, s1, 0
	global_load_dwordx4 v[162:165], v8, s[0:1] nt
	global_load_dwordx4 v[212:215], v8, s[0:1] offset:256 nt
	s_add_u32 s0, s0, 0x2000
	s_addc_u32 s1, s1, 0
	global_load_dwordx4 v[166:169], v8, s[0:1] nt
	global_load_dwordx4 v[216:219], v8, s[0:1] offset:256 nt
	s_add_u32 s0, s0, 0x2000
	s_addc_u32 s1, s1, 0
	global_load_dwordx4 v[170:173], v8, s[0:1] nt
	global_load_dwordx4 v[220:223], v8, s[0:1] offset:256 nt
	s_add_u32 s0, s0, 0x2000
	s_addc_u32 s1, s1, 0
	global_load_dwordx4 v[174:177], v8, s[0:1] nt
	global_load_dwordx4 v[224:227], v8, s[0:1] offset:256 nt
	s_add_u32 s0, s0, 0x2000
	s_addc_u32 s1, s1, 0
	global_load_dwordx4 v[178:181], v8, s[0:1] nt
	global_load_dwordx4 v[228:231], v8, s[0:1] offset:256 nt
	s_add_u32 s0, s0, 0x2000
	s_addc_u32 s1, s1, 0
	global_load_dwordx4 v[182:185], v8, s[0:1] nt
	global_load_dwordx4 v[232:235], v8, s[0:1] offset:256 nt
	s_add_u32 s0, s0, 0x2000
	s_addc_u32 s1, s1, 0
	global_load_dwordx4 v[186:189], v8, s[0:1] nt
	global_load_dwordx4 v[236:239], v8, s[0:1] offset:256 nt
	s_add_u32 s0, s0, 0x2000
	s_addc_u32 s1, s1, 0
	global_load_dwordx4 v[190:193], v8, s[0:1] nt
	global_load_dwordx4 v[240:243], v8, s[0:1] offset:256 nt
	s_add_u32 s0, s0, 0x2000
	s_addc_u32 s1, s1, 0
	global_load_dwordx4 v[194:197], v8, s[0:1] nt
	global_load_dwordx4 v[244:247], v8, s[0:1] offset:256 nt
	s_add_u32 s0, s0, 0x2000
	s_addc_u32 s1, s1, 0
	global_load_dwordx4 v[198:201], v8, s[0:1] nt
	global_load_dwordx4 v[248:251], v8, s[0:1] offset:256 nt
	s_add_u32 s0, s0, 0x2000
	s_addc_u32 s1, s1, 0
	global_load_dwordx4 v[130:133], v8, s[0:1] nt
	global_load_dwordx4 v[50:53], v8, s[0:1] offset:256 nt
	s_add_u32 s0, s0, 0x2000
	s_addc_u32 s1, s1, 0
	global_load_dwordx4 v[134:137], v8, s[0:1] nt
	global_load_dwordx4 v[54:57], v8, s[0:1] offset:256 nt
	s_add_u32 s0, s0, 0x2000
	s_addc_u32 s1, s1, 0
	global_load_dwordx4 v[138:141], v8, s[0:1] nt
	global_load_dwordx4 v[58:61], v8, s[0:1] offset:256 nt
	s_add_u32 s0, s0, 0x2000
	s_addc_u32 s1, s1, 0
	global_load_dwordx4 v[142:145], v8, s[0:1] nt
	global_load_dwordx4 v[62:65], v8, s[0:1] offset:256 nt
	s_mov_b64 exec, 1
	global_atomic_add v18, v16, v17, s[6:7] sc0
	s_mov_b64 exec, -1
	s_waitcnt vmcnt(1)
	v_cvt_pk_bf16_f32 v20, v154, v158
	v_cvt_pk_bf16_f32 v21, v162, v166
	v_cvt_pk_bf16_f32 v22, v170, v174
	v_cvt_pk_bf16_f32 v23, v178, v182
	global_store_dwordx4 v12, v[20:23], s[2:3]
	v_cvt_pk_bf16_f32 v24, v186, v190
	v_cvt_pk_bf16_f32 v25, v194, v198
	v_cvt_pk_bf16_f32 v26, v130, v134
	v_cvt_pk_bf16_f32 v27, v138, v142
	global_store_dwordx4 v12, v[24:27], s[2:3] offset:16
	v_cvt_pk_bf16_f32 v28, v155, v159
	v_cvt_pk_bf16_f32 v29, v163, v167
	v_cvt_pk_bf16_f32 v30, v171, v175
	v_cvt_pk_bf16_f32 v31, v179, v183
	global_store_dwordx4 v13, v[28:31], s[2:3]
	v_cvt_pk_bf16_f32 v32, v187, v191
	v_cvt_pk_bf16_f32 v33, v195, v199
	v_cvt_pk_bf16_f32 v34, v131, v135
	v_cvt_pk_bf16_f32 v35, v139, v143
	global_store_dwordx4 v13, v[32:35], s[2:3] offset:16
	v_cvt_pk_bf16_f32 v36, v156, v160
	v_cvt_pk_bf16_f32 v37, v164, v168
	v_cvt_pk_bf16_f32 v38, v172, v176
	v_cvt_pk_bf16_f32 v39, v180, v184
	global_store_dwordx4 v14, v[36:39], s[2:3]
	v_cvt_pk_bf16_f32 v40, v188, v192
	v_cvt_pk_bf16_f32 v41, v196, v200
	v_cvt_pk_bf16_f32 v42, v132, v136
	v_cvt_pk_bf16_f32 v43, v140, v144
	global_store_dwordx4 v14, v[40:43], s[2:3] offset:16
	v_cvt_pk_bf16_f32 v20, v157, v161
	v_cvt_pk_bf16_f32 v21, v165, v169
	v_cvt_pk_bf16_f32 v22, v173, v177
	v_cvt_pk_bf16_f32 v23, v181, v185
	global_store_dwordx4 v15, v[20:23], s[2:3]
	v_cvt_pk_bf16_f32 v24, v189, v193
	v_cvt_pk_bf16_f32 v25, v197, v201
	v_cvt_pk_bf16_f32 v26, v133, v137
	v_cvt_pk_bf16_f32 v27, v141, v145
	global_store_dwordx4 v15, v[24:27], s[2:3] offset:16
	v_cvt_pk_bf16_f32 v28, v204, v208
	v_cvt_pk_bf16_f32 v29, v212, v216
	v_cvt_pk_bf16_f32 v30, v220, v224
	v_cvt_pk_bf16_f32 v31, v228, v232
	global_store_dwordx4 v12, v[28:31], s[4:5]
	v_cvt_pk_bf16_f32 v32, v236, v240
	v_cvt_pk_bf16_f32 v33, v244, v248
	v_cvt_pk_bf16_f32 v34, v50, v54
	v_cvt_pk_bf16_f32 v35, v58, v62
	global_store_dwordx4 v12, v[32:35], s[4:5] offset:16
	v_cvt_pk_bf16_f32 v36, v205, v209
	v_cvt_pk_bf16_f32 v37, v213, v217
	v_cvt_pk_bf16_f32 v38, v221, v225
	v_cvt_pk_bf16_f32 v39, v229, v233
	global_store_dwordx4 v13, v[36:39], s[4:5]
	v_cvt_pk_bf16_f32 v40, v237, v241
	v_cvt_pk_bf16_f32 v41, v245, v249
	v_cvt_pk_bf16_f32 v42, v51, v55
	v_cvt_pk_bf16_f32 v43, v59, v63
	global_store_dwordx4 v13, v[40:43], s[4:5] offset:16
	v_cvt_pk_bf16_f32 v20, v206, v210
	v_cvt_pk_bf16_f32 v21, v214, v218
	v_cvt_pk_bf16_f32 v22, v222, v226
	v_cvt_pk_bf16_f32 v23, v230, v234
	global_store_dwordx4 v14, v[20:23], s[4:5]
	v_cvt_pk_bf16_f32 v24, v238, v242
	v_cvt_pk_bf16_f32 v25, v246, v250
	v_cvt_pk_bf16_f32 v26, v52, v56
	v_cvt_pk_bf16_f32 v27, v60, v64
	global_store_dwordx4 v14, v[24:27], s[4:5] offset:16
	v_cvt_pk_bf16_f32 v28, v207, v211
	v_cvt_pk_bf16_f32 v29, v215, v219
	v_cvt_pk_bf16_f32 v30, v223, v227
	v_cvt_pk_bf16_f32 v31, v231, v235
	global_store_dwordx4 v15, v[28:31], s[4:5]
	v_cvt_pk_bf16_f32 v32, v239, v243
	v_cvt_pk_bf16_f32 v33, v247, v251
	v_cvt_pk_bf16_f32 v34, v53, v57
	v_cvt_pk_bf16_f32 v35, v61, v65
	global_store_dwordx4 v15, v[32:35], s[4:5] offset:16
	s_waitcnt vmcnt(16)
	s_branch .Lw1d_loop
.Lw1d_done2:
	v_lshlrev_b32_e32 v6, 4, v0
	v_add_u32_e32 v7, 0x10000, v6
	ds_read_b128 v[66:69], v6 offset:0
	ds_read_b128 v[70:73], v6 offset:8192
	ds_read_b128 v[74:77], v6 offset:16384
	ds_read_b128 v[78:81], v6 offset:24576
	ds_read_b128 v[82:85], v6 offset:32768
	ds_read_b128 v[86:89], v6 offset:40960
	ds_read_b128 v[90:93], v6 offset:49152
	ds_read_b128 v[94:97], v6 offset:57344
	ds_read_b128 v[98:101], v7 offset:0
	ds_read_b128 v[102:105], v7 offset:8192
	ds_read_b128 v[106:109], v7 offset:16384
	ds_read_b128 v[110:113], v7 offset:24576
	ds_read_b128 v[114:117], v7 offset:32768
	ds_read_b128 v[118:121], v7 offset:40960
	ds_read_b128 v[122:125], v7 offset:49152
	ds_read_b128 v[126:129], v7 offset:57344
	s_waitcnt lgkmcnt(0)
